# rw_finish tile hand-written: 2 tokens per thread, all loads of a token in flight, second token's loads overlap the first token's arithmetic
# speedup vs baseline: 1.0039x; 1.0039x over previous
; DI int otid() { int t = threadIdx.x & 255; asm volatile("" : "+v"(t)); return t; }
; DI int oidx(int i) { asm volatile("" : "+s"(i)); return i; }
; DN void rw_finish_tile(const Params& p, int l, int tile, char* smem) {
;   const bfr* P = (const bfr*)(p.ws + OFF_P);
;   const bfr* RWIN = (const bfr*)(p.ws + OFF_RWIN);
;   const bfr* Y0 = (const bfr*)(p.ws + OFF_RWY);
;   const bfr* Y1 = Y0 + (size_t)MR * 256;
;   bfr* O = (bfr*)(p.ws + OFF_HO);
;   const float* mu = p.in[oidx(10)] + (size_t)l * 2 * 1152;
;   const int tid = otid();
;   const int c0 = (tid & 31) * 8;
;   float lng[8], lnb[8], rk[8], kaw[8];
;   load8f(p.in[oidx(19)] + l * 256 + c0, lng); load8f(p.in[oidx(20)] + l * 256 + c0, lnb);
;   load8f(p.in[oidx(18)] + l * 256 + c0, rk); load8f(p.in[oidx(17)] + l * 256 + c0, kaw);
; #pragma unroll 1
;   for (int ps = 0; ps < 2; ++ps) {
;     const int m = tile * 16 + ps * 8 + (tid >> 5), t = m % TT;
;     float y0[8], y1[8], af[8], ab[8], gt[8], rr[8], kx[8], vx[8];
;     unpack8(*(const u32x4*)(Y0 + (size_t)m * 256 + c0), y0);
;     unpack8(*(const u32x4*)(Y1 + (size_t)m * 256 + c0), y1);
;     unpack8(*(const u32x4*)(RWIN + ((size_t)2 * MR + m) * 256 + c0), af);
;     unpack8(*(const u32x4*)(RWIN + ((size_t)3 * MR + m) * 256 + c0), ab);
;     unpack8(*(const u32x4*)(RWIN + ((size_t)4 * MR + m) * 256 + c0), gt);
;     shifted_load8(P, m, t, c0, mu, rr);
;     shifted_load8(P, m, t, 256 + c0, mu, kx);
;     shifted_load8(P, m, t, 512 + c0, mu, vx);
.LBB0_1093:
	s_andn2_b64 vcc, exec, s[2:3]
	s_cbranch_vccnz .LBB0_1001
	s_lshl_b32 s2, s12, 4
	s_mul_hi_i32 s3, s2, 0x38e38e39
	s_lshr_b32 s4, s3, 31
	s_ashr_i32 s3, s3, 9
	s_add_i32 s3, s3, s4
	s_mulk_i32 s3, 0x900
	s_sub_i32 s3, s2, s3
	s_cmpk_lt_i32 s3, 0x800
	s_cselect_b64 s[4:5], -1, 0
	s_or_b64 s[4:5], s[92:93], s[4:5]
	s_andn2_b64 vcc, exec, s[4:5]
	s_cbranch_vccnz .LBB0_1001
	s_load_dwordx2 s[2:3], s[0:1], 0x108
	s_load_dwordx4 s[4:7], s[0:1], 0x88
	v_readlane_b32 s8, v253, 13
	s_lshl_b32 s9, s12, 4
	s_mul_hi_u32 s98, s9, 0x38e38e39
	s_lshr_b32 s98, s98, 9
	s_mulk_i32 s98, 0x900
	s_sub_u32 s98, s9, s98
	v_and_b32_e32 v120, 31, v183
	v_lshrrev_b32_e32 v121, 5, v183
	v_lshlrev_b32_e32 v122, 4, v120
	v_lshlrev_b32_e32 v123, 5, v120
	v_add_u32_e32 v124, s9, v121
	v_mad_u32_u24 v126, v124, s88, v122
	v_add_u32_e32 v125, 0xffffe680, v126
	v_add_u32_e32 v127, 0x1980, v126
	v_add_u32_e32 v128, 0xb280, v126
	v_add_u32_e32 v129, 0xcc00, v126
	v_add_u32_e32 v130, 0xe580, v126
	v_lshl_add_u32 v131, v124, 9, v122
	v_add_u32_e32 v132, 0x1c4fc900, v131
	v_add_u32_e32 v133, 0x17cfc900, v131
	v_add_u32_e32 v134, 0x18efc900, v131
	v_add_u32_e32 v135, 0x1a0fc900, v131
	v_add_u32_e32 v131, 0x1b2fc900, v131
	v_lshl_add_u32 v180, v124, 11, v122
	v_add_u32_e32 v180, 0x2b7c100, v180
	v_add_u32_e32 v181, 0x4000, v180
	v_mov_b32_e32 v32, 0
	v_mov_b32_e32 v100, 0
	v_mov_b32_e32 v33, 0
	v_mov_b32_e32 v101, 0
	v_mov_b32_e32 v34, 0
	v_mov_b32_e32 v102, 0
	v_mov_b32_e32 v35, 0
	v_mov_b32_e32 v103, 0
	v_mov_b32_e32 v36, 0
	v_mov_b32_e32 v104, 0
	v_mov_b32_e32 v37, 0
	v_mov_b32_e32 v105, 0
	v_mov_b32_e32 v38, 0
	v_mov_b32_e32 v106, 0
	v_mov_b32_e32 v39, 0
	v_mov_b32_e32 v107, 0
	v_mov_b32_e32 v40, 0
	v_mov_b32_e32 v108, 0
	v_mov_b32_e32 v41, 0
	v_mov_b32_e32 v109, 0
	v_mov_b32_e32 v42, 0
	v_mov_b32_e32 v110, 0
	v_mov_b32_e32 v43, 0
	v_mov_b32_e32 v111, 0
	s_waitcnt lgkmcnt(0)
	global_load_dwordx4 v[0:3], v131, s[2:3] offset:-2048
	global_load_dwordx4 v[4:7], v132, s[2:3] offset:-2048
	global_load_dwordx4 v[8:11], v133, s[2:3] offset:-2048
	global_load_dwordx4 v[12:15], v134, s[2:3] offset:-2048
	global_load_dwordx4 v[16:19], v135, s[2:3] offset:-2048
	global_load_dwordx4 v[20:23], v126, s[84:85]
	global_load_dwordx4 v[24:27], v126, s[84:85] offset:512
	global_load_dwordx4 v[28:31], v126, s[84:85] offset:1024
	v_cmp_ne_u32_e32 vcc, 0, v121
	s_andn2_b32 s99, s98, 0x800
	s_cselect_b64 vcc, exec, vcc
	s_mov_b64 exec, vcc
	global_load_dwordx4 v[32:35], v125, s[84:85]
	global_load_dwordx4 v[36:39], v125, s[84:85] offset:512
	global_load_dwordx4 v[40:43], v125, s[84:85] offset:1024
	s_mov_b64 exec, -1
	global_load_dwordx4 v[44:47], v127, s[84:85]
	global_load_dwordx4 v[48:51], v127, s[84:85] offset:512
	global_load_dwordx4 v[52:55], v127, s[84:85] offset:1024
	s_lshl_b32 s99, s8, 10
	s_add_u32 s4, s4, s99
	s_addc_u32 s5, s5, 0
	s_add_u32 s6, s6, s99
	s_addc_u32 s7, s7, 0
	global_load_dwordx4 v[112:115], v123, s[4:5]
	global_load_dwordx4 v[116:119], v123, s[4:5] offset:16
	global_load_dwordx4 v[172:175], v123, s[6:7]
	global_load_dwordx4 v[176:179], v123, s[6:7] offset:16
	s_load_dwordx4 s[4:7], s[0:1], 0x98
	s_waitcnt lgkmcnt(0)
	s_add_u32 s4, s4, s99
	s_addc_u32 s5, s5, 0
	s_add_u32 s6, s6, s99
	s_addc_u32 s7, s7, 0
	global_load_dwordx4 v[156:159], v123, s[4:5]
	global_load_dwordx4 v[160:163], v123, s[4:5] offset:16
	global_load_dwordx4 v[164:167], v123, s[6:7]
	global_load_dwordx4 v[168:171], v123, s[6:7] offset:16
	s_load_dwordx2 s[4:5], s[0:1], 0x50
	s_mulk_i32 s8, 0x2400
	s_waitcnt lgkmcnt(0)
	s_add_u32 s4, s4, s8
	s_addc_u32 s5, s5, 0
	s_add_u32 s6, s4, 0x1200
	s_addc_u32 s7, s5, 0
	global_load_dwordx4 v[202:205], v123, s[4:5] offset:0
	global_load_dwordx4 v[206:209], v123, s[4:5] offset:16
	global_load_dwordx4 v[210:213], v123, s[6:7] offset:0
	global_load_dwordx4 v[214:217], v123, s[6:7] offset:16
	global_load_dwordx4 v[218:221], v123, s[4:5] offset:1024
	global_load_dwordx4 v[222:225], v123, s[4:5] offset:1040
	global_load_dwordx4 v[226:229], v123, s[6:7] offset:1024
	global_load_dwordx4 v[230:233], v123, s[6:7] offset:1040
	global_load_dwordx4 v[234:237], v123, s[4:5] offset:2048
	global_load_dwordx4 v[238:241], v123, s[4:5] offset:2064
	global_load_dwordx4 v[242:245], v123, s[6:7] offset:2048
	global_load_dwordx4 v[246:249], v123, s[6:7] offset:2064
	global_load_dwordx4 v[56:59], v131, s[2:3] offset:2048
	global_load_dwordx4 v[60:63], v132, s[2:3] offset:2048
	global_load_dwordx4 v[64:67], v133, s[2:3] offset:2048
	global_load_dwordx4 v[68:71], v134, s[2:3] offset:2048
	global_load_dwordx4 v[72:75], v135, s[2:3] offset:2048
	global_load_dwordx4 v[76:79], v129, s[84:85]
	global_load_dwordx4 v[80:83], v129, s[84:85] offset:512
	global_load_dwordx4 v[84:87], v129, s[84:85] offset:1024
	global_load_dwordx4 v[88:91], v128, s[84:85]
	global_load_dwordx4 v[92:95], v128, s[84:85] offset:512
	global_load_dwordx4 v[96:99], v128, s[84:85] offset:1024
	v_cmp_ne_u32_e32 vcc, 7, v121
	s_sub_u32 s99, s98, 0x7f0
	s_andn2_b32 s99, s99, 0x100
	s_cselect_b64 vcc, exec, vcc
	s_mov_b64 exec, vcc
	global_load_dwordx4 v[100:103], v130, s[84:85]
	global_load_dwordx4 v[104:107], v130, s[84:85] offset:512
	global_load_dwordx4 v[108:111], v130, s[84:85] offset:1024
	s_mov_b64 exec, -1
	s_waitcnt vmcnt(14)
; DI void shifted_load8(const bfr* P, int m, int t, int col, const float* mu, float (&o)[8]) {
;   const bfr* row = P + (size_t)m * PW + col;
;   const bool hp = (t != 0 && t != TL), hn = (t != TL - 1 && t != TT - 1);
;   const u32x4 cur = *(const u32x4*)row;
;   u32x4 prv = {0u, 0u, 0u, 0u}, nxt = {0u, 0u, 0u, 0u};
;   if (hp) prv = *(const u32x4*)(row - PW);
;   if (hn) nxt = *(const u32x4*)(row + PW);
;   float x[8], xp[8], xn[8], m0v[8], m1v[8];
;   unpack8(cur, x); unpack8(prv, xp); unpack8(nxt, xn);
;   load8f(mu + col, m0v); load8f(mu + 1152 + col, m1v);
; #pragma unroll
;   for (int e = 0; e < 8; ++e) o[e] = x[e] + m0v[e] * (xp[e] - x[e]) + m1v[e] * (xn[e] - x[e]);
; }
; DN void rw_finish_tile(const Params& p, int l, int tile, char* smem) {
;     ...
;     shifted_load8(P, m, t, c0, mu, rr);
;     shifted_load8(P, m, t, 256 + c0, mu, kx);
;     shifted_load8(P, m, t, 512 + c0, mu, vx);
	v_lshlrev_b32_e32 v146, 16, v20
	v_and_b32_e32 v147, 0xffff0000, v20
	v_lshlrev_b32_e32 v148, 16, v32
	v_and_b32_e32 v149, 0xffff0000, v32
	v_lshlrev_b32_e32 v150, 16, v44
	v_and_b32_e32 v151, 0xffff0000, v44
	v_pk_add_f32 v[148:149], v[148:149], v[146:147] neg_lo:[0,1] neg_hi:[0,1]
	v_pk_add_f32 v[150:151], v[150:151], v[146:147] neg_lo:[0,1] neg_hi:[0,1]
	v_pk_fma_f32 v[146:147], v[148:149], v[202:203], v[146:147]
	v_pk_fma_f32 v[120:121], v[150:151], v[210:211], v[146:147]
	v_lshlrev_b32_e32 v146, 16, v21
	v_and_b32_e32 v147, 0xffff0000, v21
	v_lshlrev_b32_e32 v148, 16, v33
	v_and_b32_e32 v149, 0xffff0000, v33
	v_lshlrev_b32_e32 v150, 16, v45
	v_and_b32_e32 v151, 0xffff0000, v45
	v_pk_add_f32 v[148:149], v[148:149], v[146:147] neg_lo:[0,1] neg_hi:[0,1]
	v_pk_add_f32 v[150:151], v[150:151], v[146:147] neg_lo:[0,1] neg_hi:[0,1]
	v_pk_fma_f32 v[146:147], v[148:149], v[204:205], v[146:147]
	v_pk_fma_f32 v[122:123], v[150:151], v[212:213], v[146:147]
	v_lshlrev_b32_e32 v146, 16, v22
	v_and_b32_e32 v147, 0xffff0000, v22
	v_lshlrev_b32_e32 v148, 16, v34
	v_and_b32_e32 v149, 0xffff0000, v34
	v_lshlrev_b32_e32 v150, 16, v46
	v_and_b32_e32 v151, 0xffff0000, v46
	v_pk_add_f32 v[148:149], v[148:149], v[146:147] neg_lo:[0,1] neg_hi:[0,1]
	v_pk_add_f32 v[150:151], v[150:151], v[146:147] neg_lo:[0,1] neg_hi:[0,1]
	v_pk_fma_f32 v[146:147], v[148:149], v[206:207], v[146:147]
	v_pk_fma_f32 v[124:125], v[150:151], v[214:215], v[146:147]
	v_lshlrev_b32_e32 v146, 16, v23
	v_and_b32_e32 v147, 0xffff0000, v23
	v_lshlrev_b32_e32 v148, 16, v35
	v_and_b32_e32 v149, 0xffff0000, v35
	v_lshlrev_b32_e32 v150, 16, v47
	v_and_b32_e32 v151, 0xffff0000, v47
	v_pk_add_f32 v[148:149], v[148:149], v[146:147] neg_lo:[0,1] neg_hi:[0,1]
	v_pk_add_f32 v[150:151], v[150:151], v[146:147] neg_lo:[0,1] neg_hi:[0,1]
	v_pk_fma_f32 v[146:147], v[148:149], v[208:209], v[146:147]
	v_pk_fma_f32 v[126:127], v[150:151], v[216:217], v[146:147]
	v_lshlrev_b32_e32 v146, 16, v24
	v_and_b32_e32 v147, 0xffff0000, v24
	v_lshlrev_b32_e32 v148, 16, v36
	v_and_b32_e32 v149, 0xffff0000, v36
	v_lshlrev_b32_e32 v150, 16, v48
	v_and_b32_e32 v151, 0xffff0000, v48
	v_pk_add_f32 v[148:149], v[148:149], v[146:147] neg_lo:[0,1] neg_hi:[0,1]
	v_pk_add_f32 v[150:151], v[150:151], v[146:147] neg_lo:[0,1] neg_hi:[0,1]
	v_pk_fma_f32 v[146:147], v[148:149], v[218:219], v[146:147]
	v_pk_fma_f32 v[128:129], v[150:151], v[226:227], v[146:147]
	v_lshlrev_b32_e32 v146, 16, v25
	v_and_b32_e32 v147, 0xffff0000, v25
	v_lshlrev_b32_e32 v148, 16, v37
	v_and_b32_e32 v149, 0xffff0000, v37
	v_lshlrev_b32_e32 v150, 16, v49
	v_and_b32_e32 v151, 0xffff0000, v49
	v_pk_add_f32 v[148:149], v[148:149], v[146:147] neg_lo:[0,1] neg_hi:[0,1]
	v_pk_add_f32 v[150:151], v[150:151], v[146:147] neg_lo:[0,1] neg_hi:[0,1]
	v_pk_fma_f32 v[146:147], v[148:149], v[220:221], v[146:147]
	v_pk_fma_f32 v[130:131], v[150:151], v[228:229], v[146:147]
	v_lshlrev_b32_e32 v146, 16, v26
	v_and_b32_e32 v147, 0xffff0000, v26
	v_lshlrev_b32_e32 v148, 16, v38
	v_and_b32_e32 v149, 0xffff0000, v38
	v_lshlrev_b32_e32 v150, 16, v50
	v_and_b32_e32 v151, 0xffff0000, v50
	v_pk_add_f32 v[148:149], v[148:149], v[146:147] neg_lo:[0,1] neg_hi:[0,1]
	v_pk_add_f32 v[150:151], v[150:151], v[146:147] neg_lo:[0,1] neg_hi:[0,1]
	v_pk_fma_f32 v[146:147], v[148:149], v[222:223], v[146:147]
	v_pk_fma_f32 v[132:133], v[150:151], v[230:231], v[146:147]
	v_lshlrev_b32_e32 v146, 16, v27
	v_and_b32_e32 v147, 0xffff0000, v27
	v_lshlrev_b32_e32 v148, 16, v39
	v_and_b32_e32 v149, 0xffff0000, v39
	v_lshlrev_b32_e32 v150, 16, v51
	v_and_b32_e32 v151, 0xffff0000, v51
	v_pk_add_f32 v[148:149], v[148:149], v[146:147] neg_lo:[0,1] neg_hi:[0,1]
	v_pk_add_f32 v[150:151], v[150:151], v[146:147] neg_lo:[0,1] neg_hi:[0,1]
	v_pk_fma_f32 v[146:147], v[148:149], v[224:225], v[146:147]
	v_pk_fma_f32 v[134:135], v[150:151], v[232:233], v[146:147]
	v_lshlrev_b32_e32 v146, 16, v28
	v_and_b32_e32 v147, 0xffff0000, v28
	v_lshlrev_b32_e32 v148, 16, v40
	v_and_b32_e32 v149, 0xffff0000, v40
	v_lshlrev_b32_e32 v150, 16, v52
	v_and_b32_e32 v151, 0xffff0000, v52
	v_pk_add_f32 v[148:149], v[148:149], v[146:147] neg_lo:[0,1] neg_hi:[0,1]
	v_pk_add_f32 v[150:151], v[150:151], v[146:147] neg_lo:[0,1] neg_hi:[0,1]
	v_pk_fma_f32 v[146:147], v[148:149], v[234:235], v[146:147]
	v_pk_fma_f32 v[136:137], v[150:151], v[242:243], v[146:147]
	v_lshlrev_b32_e32 v146, 16, v29
	v_and_b32_e32 v147, 0xffff0000, v29
	v_lshlrev_b32_e32 v148, 16, v41
	v_and_b32_e32 v149, 0xffff0000, v41
	v_lshlrev_b32_e32 v150, 16, v53
	v_and_b32_e32 v151, 0xffff0000, v53
	v_pk_add_f32 v[148:149], v[148:149], v[146:147] neg_lo:[0,1] neg_hi:[0,1]
	v_pk_add_f32 v[150:151], v[150:151], v[146:147] neg_lo:[0,1] neg_hi:[0,1]
	v_pk_fma_f32 v[146:147], v[148:149], v[236:237], v[146:147]
	v_pk_fma_f32 v[138:139], v[150:151], v[244:245], v[146:147]
	v_lshlrev_b32_e32 v146, 16, v30
	v_and_b32_e32 v147, 0xffff0000, v30
	v_lshlrev_b32_e32 v148, 16, v42
	v_and_b32_e32 v149, 0xffff0000, v42
	v_lshlrev_b32_e32 v150, 16, v54
	v_and_b32_e32 v151, 0xffff0000, v54
	v_pk_add_f32 v[148:149], v[148:149], v[146:147] neg_lo:[0,1] neg_hi:[0,1]
	v_pk_add_f32 v[150:151], v[150:151], v[146:147] neg_lo:[0,1] neg_hi:[0,1]
	v_pk_fma_f32 v[146:147], v[148:149], v[238:239], v[146:147]
	v_pk_fma_f32 v[140:141], v[150:151], v[246:247], v[146:147]
	v_lshlrev_b32_e32 v146, 16, v31
	v_and_b32_e32 v147, 0xffff0000, v31
	v_lshlrev_b32_e32 v148, 16, v43
	v_and_b32_e32 v149, 0xffff0000, v43
	v_lshlrev_b32_e32 v150, 16, v55
	v_and_b32_e32 v151, 0xffff0000, v55
	v_pk_add_f32 v[148:149], v[148:149], v[146:147] neg_lo:[0,1] neg_hi:[0,1]
	v_pk_add_f32 v[150:151], v[150:151], v[146:147] neg_lo:[0,1] neg_hi:[0,1]
; DI float red8(float x) { x += dppf<0xB1>(x); x += dppf<0x4E>(x); x += dppf<0x141>(x); return x; }
; DN void rw_finish_tile(const Params& p, int l, int tile, char* smem) {
;     ...
;     float sy = 0.f;
; #pragma unroll
;     for (int e = 0; e < 8; ++e) { y0[e] += y1[e]; sy += y0[e]; }
;     const float mean = red8(sy) * (1.f / 64.f);
;     float sv = 0.f, sd = 0.f;
; #pragma unroll
;     for (int e = 0; e < 8; ++e) {
;       const float dl = y0[e] - mean; y0[e] = dl; sv += dl * dl;
;       const float kds = kx[e] * (1.f + (af[e] - 1.f) * kaw[e]) + kx[e] * (1.f + (ab[e] - 1.f) * kaw[e]);
;       sd += rr[e] * rk[e] * kds;
;     }
;     const float var = red8(sv) * (1.f / 64.f);
;     const float sdot = red8(sd);
;     const float rs = rsqrtf(var + 64e-5f);
;     float ov[8];
; #pragma unroll
;     for (int e = 0; e < 8; ++e) ov[e] = (y0[e] * rs * lng[e] + lnb[e] + sdot * vx[e]) * gt[e];
	v_pk_fma_f32 v[146:147], v[148:149], v[240:241], v[146:147]
	v_pk_fma_f32 v[142:143], v[150:151], v[248:249], v[146:147]
	v_lshlrev_b32_e32 v146, 16, v0
	v_and_b32_e32 v147, 0xffff0000, v0
	v_lshlrev_b32_e32 v148, 16, v4
	v_and_b32_e32 v149, 0xffff0000, v4
	v_pk_add_f32 v[20:21], v[146:147], v[148:149]
	v_lshlrev_b32_e32 v146, 16, v1
	v_and_b32_e32 v147, 0xffff0000, v1
	v_lshlrev_b32_e32 v148, 16, v5
	v_and_b32_e32 v149, 0xffff0000, v5
	v_pk_add_f32 v[22:23], v[146:147], v[148:149]
	v_lshlrev_b32_e32 v146, 16, v2
	v_and_b32_e32 v147, 0xffff0000, v2
	v_lshlrev_b32_e32 v148, 16, v6
	v_and_b32_e32 v149, 0xffff0000, v6
	v_pk_add_f32 v[24:25], v[146:147], v[148:149]
	v_lshlrev_b32_e32 v146, 16, v3
	v_and_b32_e32 v147, 0xffff0000, v3
	v_lshlrev_b32_e32 v148, 16, v7
	v_and_b32_e32 v149, 0xffff0000, v7
	v_pk_add_f32 v[26:27], v[146:147], v[148:149]
	v_add_f32_e32 v152, 0, v20
	v_add_f32_e32 v152, v21, v152
	v_add_f32_e32 v152, v22, v152
	v_add_f32_e32 v152, v23, v152
	v_add_f32_e32 v152, v24, v152
	v_add_f32_e32 v152, v25, v152
	v_add_f32_e32 v152, v26, v152
	v_add_f32_e32 v152, v27, v152
	s_nop 1
	v_add_f32_dpp v152, v152, v152 quad_perm:[1,0,3,2] row_mask:0xf bank_mask:0xf bound_ctrl:1
	s_nop 1
	v_add_f32_dpp v152, v152, v152 quad_perm:[2,3,0,1] row_mask:0xf bank_mask:0xf bound_ctrl:1
	s_nop 1
	v_add_f32_dpp v152, v152, v152 row_half_mirror row_mask:0xf bank_mask:0xf bound_ctrl:1
	v_mul_f32_e32 v154, 0x3c800000, v152
	v_pk_add_f32 v[20:21], v[20:21], v[154:155] op_sel_hi:[1,0] neg_lo:[0,1] neg_hi:[0,1]
	v_pk_add_f32 v[22:23], v[22:23], v[154:155] op_sel_hi:[1,0] neg_lo:[0,1] neg_hi:[0,1]
	v_pk_add_f32 v[24:25], v[24:25], v[154:155] op_sel_hi:[1,0] neg_lo:[0,1] neg_hi:[0,1]
	v_pk_add_f32 v[26:27], v[26:27], v[154:155] op_sel_hi:[1,0] neg_lo:[0,1] neg_hi:[0,1]
	v_pk_mul_f32 v[146:147], v[20:21], v[20:21]
	v_add_f32_e32 v250, 0, v146
	v_add_f32_e32 v250, v147, v250
	v_pk_mul_f32 v[146:147], v[22:23], v[22:23]
	v_add_f32_e32 v250, v146, v250
	v_add_f32_e32 v250, v147, v250
	v_pk_mul_f32 v[146:147], v[24:25], v[24:25]
	v_add_f32_e32 v250, v146, v250
	v_add_f32_e32 v250, v147, v250
	v_pk_mul_f32 v[146:147], v[26:27], v[26:27]
	v_add_f32_e32 v250, v146, v250
	v_add_f32_e32 v250, v147, v250
	v_lshlrev_b32_e32 v146, 16, v8
	v_and_b32_e32 v147, 0xffff0000, v8
	v_lshlrev_b32_e32 v148, 16, v12
	v_and_b32_e32 v149, 0xffff0000, v12
	v_pk_add_f32 v[146:147], v[146:147], -1.0 op_sel_hi:[1,0]
	v_pk_add_f32 v[148:149], v[148:149], -1.0 op_sel_hi:[1,0]
	v_pk_fma_f32 v[146:147], v[112:113], v[146:147], 1.0 op_sel_hi:[1,1,0]
	v_pk_fma_f32 v[148:149], v[112:113], v[148:149], 1.0 op_sel_hi:[1,1,0]
	v_pk_mul_f32 v[146:147], v[146:147], v[128:129]
	v_pk_fma_f32 v[148:149], v[148:149], v[128:129], v[146:147]
	v_pk_mul_f32 v[150:151], v[172:173], v[120:121]
	v_pk_mul_f32 v[150:151], v[150:151], v[148:149]
	v_add_f32_e32 v251, 0, v150
	v_add_f32_e32 v251, v151, v251
	v_lshlrev_b32_e32 v146, 16, v9
	v_and_b32_e32 v147, 0xffff0000, v9
	v_lshlrev_b32_e32 v148, 16, v13
	v_and_b32_e32 v149, 0xffff0000, v13
	v_pk_add_f32 v[146:147], v[146:147], -1.0 op_sel_hi:[1,0]
	v_pk_add_f32 v[148:149], v[148:149], -1.0 op_sel_hi:[1,0]
	v_pk_fma_f32 v[146:147], v[114:115], v[146:147], 1.0 op_sel_hi:[1,1,0]
	v_pk_fma_f32 v[148:149], v[114:115], v[148:149], 1.0 op_sel_hi:[1,1,0]
	v_pk_mul_f32 v[146:147], v[146:147], v[130:131]
	v_pk_fma_f32 v[148:149], v[148:149], v[130:131], v[146:147]
	v_pk_mul_f32 v[150:151], v[174:175], v[122:123]
	v_pk_mul_f32 v[150:151], v[150:151], v[148:149]
	v_add_f32_e32 v251, v150, v251
	v_add_f32_e32 v251, v151, v251
	v_lshlrev_b32_e32 v146, 16, v10
	v_and_b32_e32 v147, 0xffff0000, v10
	v_lshlrev_b32_e32 v148, 16, v14
	v_and_b32_e32 v149, 0xffff0000, v14
	v_pk_add_f32 v[146:147], v[146:147], -1.0 op_sel_hi:[1,0]
	v_pk_add_f32 v[148:149], v[148:149], -1.0 op_sel_hi:[1,0]
	v_pk_fma_f32 v[146:147], v[116:117], v[146:147], 1.0 op_sel_hi:[1,1,0]
	v_pk_fma_f32 v[148:149], v[116:117], v[148:149], 1.0 op_sel_hi:[1,1,0]
	v_pk_mul_f32 v[146:147], v[146:147], v[132:133]
	v_pk_fma_f32 v[148:149], v[148:149], v[132:133], v[146:147]
	v_pk_mul_f32 v[150:151], v[176:177], v[124:125]
	v_pk_mul_f32 v[150:151], v[150:151], v[148:149]
	v_add_f32_e32 v251, v150, v251
	v_add_f32_e32 v251, v151, v251
	v_lshlrev_b32_e32 v146, 16, v11
	v_and_b32_e32 v147, 0xffff0000, v11
	v_lshlrev_b32_e32 v148, 16, v15
	v_and_b32_e32 v149, 0xffff0000, v15
	v_pk_add_f32 v[146:147], v[146:147], -1.0 op_sel_hi:[1,0]
	v_pk_add_f32 v[148:149], v[148:149], -1.0 op_sel_hi:[1,0]
	v_pk_fma_f32 v[146:147], v[118:119], v[146:147], 1.0 op_sel_hi:[1,1,0]
	v_pk_fma_f32 v[148:149], v[118:119], v[148:149], 1.0 op_sel_hi:[1,1,0]
	v_pk_mul_f32 v[146:147], v[146:147], v[134:135]
	v_pk_fma_f32 v[148:149], v[148:149], v[134:135], v[146:147]
	v_pk_mul_f32 v[150:151], v[178:179], v[126:127]
	v_pk_mul_f32 v[150:151], v[150:151], v[148:149]
	v_add_f32_e32 v251, v150, v251
	v_add_f32_e32 v251, v151, v251
	v_add_f32_dpp v250, v250, v250 quad_perm:[1,0,3,2] row_mask:0xf bank_mask:0xf bound_ctrl:1
	s_nop 0
	v_add_f32_dpp v251, v251, v251 quad_perm:[1,0,3,2] row_mask:0xf bank_mask:0xf bound_ctrl:1
	v_add_f32_dpp v250, v250, v250 quad_perm:[2,3,0,1] row_mask:0xf bank_mask:0xf bound_ctrl:1
	s_nop 0
	v_add_f32_dpp v251, v251, v251 quad_perm:[2,3,0,1] row_mask:0xf bank_mask:0xf bound_ctrl:1
	v_add_f32_dpp v250, v250, v250 row_half_mirror row_mask:0xf bank_mask:0xf bound_ctrl:1
	s_nop 0
	v_add_f32_dpp v251, v251, v251 row_half_mirror row_mask:0xf bank_mask:0xf bound_ctrl:1
	v_mov_b32_e32 v155, 0x3a27c5ac
	v_fmamk_f32 v250, v250, 0x3c800000, v155
	v_rsq_f32_e32 v250, v250
	v_mov_b32_e32 v152, v251
	v_pk_mul_f32 v[146:147], v[20:21], v[250:251] op_sel_hi:[1,0]
; DI unsigned pack2(float a, float b) { unsigned r; asm volatile("v_cvt_pk_bf16_f32 %0, %1, %2" : "=v"(r) : "v"(a), "v"(b)); return r; }
; DI void shifted_load8(const bfr* P, int m, int t, int col, const float* mu, float (&o)[8]) {
;   const bfr* row = P + (size_t)m * PW + col;
;   const bool hp = (t != 0 && t != TL), hn = (t != TL - 1 && t != TT - 1);
;   const u32x4 cur = *(const u32x4*)row;
;   u32x4 prv = {0u, 0u, 0u, 0u}, nxt = {0u, 0u, 0u, 0u};
;   if (hp) prv = *(const u32x4*)(row - PW);
;   if (hn) nxt = *(const u32x4*)(row + PW);
;   float x[8], xp[8], xn[8], m0v[8], m1v[8];
;   unpack8(cur, x); unpack8(prv, xp); unpack8(nxt, xn);
;   load8f(mu + col, m0v); load8f(mu + 1152 + col, m1v);
; #pragma unroll
;   for (int e = 0; e < 8; ++e) o[e] = x[e] + m0v[e] * (xp[e] - x[e]) + m1v[e] * (xn[e] - x[e]);
; }
; DN void rw_finish_tile(const Params& p, int l, int tile, char* smem) {
;     ...
;     const float rs = rsqrtf(var + 64e-5f);
;     float ov[8];
; #pragma unroll
;     for (int e = 0; e < 8; ++e) ov[e] = (y0[e] * rs * lng[e] + lnb[e] + sdot * vx[e]) * gt[e];
;     u32x4 ow; ow.x = pack2(ov[0], ov[1]); ow.y = pack2(ov[2], ov[3]); ow.z = pack2(ov[4], ov[5]); ow.w = pack2(ov[6], ov[7]);
;     *(u32x4*)(O + (size_t)m * DM + c0) = ow;
	v_pk_mul_f32 v[146:147], v[156:157], v[146:147]
	v_pk_add_f32 v[146:147], v[164:165], v[146:147]
	v_pk_mul_f32 v[148:149], v[136:137], v[152:153] op_sel_hi:[1,0]
	v_pk_add_f32 v[146:147], v[148:149], v[146:147]
	v_lshlrev_b32_e32 v148, 16, v16
	v_and_b32_e32 v149, 0xffff0000, v16
	v_pk_mul_f32 v[146:147], v[146:147], v[148:149]
	v_cvt_pk_bf16_f32 v16, v146, v147
	v_pk_mul_f32 v[146:147], v[22:23], v[250:251] op_sel_hi:[1,0]
	v_pk_mul_f32 v[146:147], v[158:159], v[146:147]
	v_pk_add_f32 v[146:147], v[166:167], v[146:147]
	v_pk_mul_f32 v[148:149], v[138:139], v[152:153] op_sel_hi:[1,0]
	v_pk_add_f32 v[146:147], v[148:149], v[146:147]
	v_lshlrev_b32_e32 v148, 16, v17
	v_and_b32_e32 v149, 0xffff0000, v17
	v_pk_mul_f32 v[146:147], v[146:147], v[148:149]
	v_cvt_pk_bf16_f32 v17, v146, v147
	v_pk_mul_f32 v[146:147], v[24:25], v[250:251] op_sel_hi:[1,0]
	v_pk_mul_f32 v[146:147], v[160:161], v[146:147]
	v_pk_add_f32 v[146:147], v[168:169], v[146:147]
	v_pk_mul_f32 v[148:149], v[140:141], v[152:153] op_sel_hi:[1,0]
	v_pk_add_f32 v[146:147], v[148:149], v[146:147]
	v_lshlrev_b32_e32 v148, 16, v18
	v_and_b32_e32 v149, 0xffff0000, v18
	v_pk_mul_f32 v[146:147], v[146:147], v[148:149]
	v_cvt_pk_bf16_f32 v18, v146, v147
	v_pk_mul_f32 v[146:147], v[26:27], v[250:251] op_sel_hi:[1,0]
	v_pk_mul_f32 v[146:147], v[162:163], v[146:147]
	v_pk_add_f32 v[146:147], v[170:171], v[146:147]
	v_pk_mul_f32 v[148:149], v[142:143], v[152:153] op_sel_hi:[1,0]
	v_pk_add_f32 v[146:147], v[148:149], v[146:147]
	v_lshlrev_b32_e32 v148, 16, v19
	v_and_b32_e32 v149, 0xffff0000, v19
	v_pk_mul_f32 v[146:147], v[146:147], v[148:149]
	v_cvt_pk_bf16_f32 v19, v146, v147
	global_store_dwordx4 v180, v[16:19], s[2:3]
	s_waitcnt vmcnt(1)
	v_lshlrev_b32_e32 v146, 16, v76
	v_and_b32_e32 v147, 0xffff0000, v76
	v_lshlrev_b32_e32 v148, 16, v88
	v_and_b32_e32 v149, 0xffff0000, v88
	v_lshlrev_b32_e32 v150, 16, v100
	v_and_b32_e32 v151, 0xffff0000, v100
	v_pk_add_f32 v[148:149], v[148:149], v[146:147] neg_lo:[0,1] neg_hi:[0,1]
	v_pk_add_f32 v[150:151], v[150:151], v[146:147] neg_lo:[0,1] neg_hi:[0,1]
	v_pk_fma_f32 v[146:147], v[148:149], v[202:203], v[146:147]
	v_pk_fma_f32 v[120:121], v[150:151], v[210:211], v[146:147]
	v_lshlrev_b32_e32 v146, 16, v77
	v_and_b32_e32 v147, 0xffff0000, v77
	v_lshlrev_b32_e32 v148, 16, v89
	v_and_b32_e32 v149, 0xffff0000, v89
	v_lshlrev_b32_e32 v150, 16, v101
	v_and_b32_e32 v151, 0xffff0000, v101
	v_pk_add_f32 v[148:149], v[148:149], v[146:147] neg_lo:[0,1] neg_hi:[0,1]
	v_pk_add_f32 v[150:151], v[150:151], v[146:147] neg_lo:[0,1] neg_hi:[0,1]
	v_pk_fma_f32 v[146:147], v[148:149], v[204:205], v[146:147]
	v_pk_fma_f32 v[122:123], v[150:151], v[212:213], v[146:147]
	v_lshlrev_b32_e32 v146, 16, v78
	v_and_b32_e32 v147, 0xffff0000, v78
	v_lshlrev_b32_e32 v148, 16, v90
	v_and_b32_e32 v149, 0xffff0000, v90
	v_lshlrev_b32_e32 v150, 16, v102
	v_and_b32_e32 v151, 0xffff0000, v102
	v_pk_add_f32 v[148:149], v[148:149], v[146:147] neg_lo:[0,1] neg_hi:[0,1]
	v_pk_add_f32 v[150:151], v[150:151], v[146:147] neg_lo:[0,1] neg_hi:[0,1]
	v_pk_fma_f32 v[146:147], v[148:149], v[206:207], v[146:147]
	v_pk_fma_f32 v[124:125], v[150:151], v[214:215], v[146:147]
	v_lshlrev_b32_e32 v146, 16, v79
	v_and_b32_e32 v147, 0xffff0000, v79
	v_lshlrev_b32_e32 v148, 16, v91
	v_and_b32_e32 v149, 0xffff0000, v91
	v_lshlrev_b32_e32 v150, 16, v103
	v_and_b32_e32 v151, 0xffff0000, v103
	v_pk_add_f32 v[148:149], v[148:149], v[146:147] neg_lo:[0,1] neg_hi:[0,1]
	v_pk_add_f32 v[150:151], v[150:151], v[146:147] neg_lo:[0,1] neg_hi:[0,1]
	v_pk_fma_f32 v[146:147], v[148:149], v[208:209], v[146:147]
	v_pk_fma_f32 v[126:127], v[150:151], v[216:217], v[146:147]
	v_lshlrev_b32_e32 v146, 16, v80
	v_and_b32_e32 v147, 0xffff0000, v80
	v_lshlrev_b32_e32 v148, 16, v92
	v_and_b32_e32 v149, 0xffff0000, v92
	v_lshlrev_b32_e32 v150, 16, v104
	v_and_b32_e32 v151, 0xffff0000, v104
	v_pk_add_f32 v[148:149], v[148:149], v[146:147] neg_lo:[0,1] neg_hi:[0,1]
	v_pk_add_f32 v[150:151], v[150:151], v[146:147] neg_lo:[0,1] neg_hi:[0,1]
	v_pk_fma_f32 v[146:147], v[148:149], v[218:219], v[146:147]
	v_pk_fma_f32 v[128:129], v[150:151], v[226:227], v[146:147]
	v_lshlrev_b32_e32 v146, 16, v81
	v_and_b32_e32 v147, 0xffff0000, v81
	v_lshlrev_b32_e32 v148, 16, v93
	v_and_b32_e32 v149, 0xffff0000, v93
	v_lshlrev_b32_e32 v150, 16, v105
	v_and_b32_e32 v151, 0xffff0000, v105
	v_pk_add_f32 v[148:149], v[148:149], v[146:147] neg_lo:[0,1] neg_hi:[0,1]
	v_pk_add_f32 v[150:151], v[150:151], v[146:147] neg_lo:[0,1] neg_hi:[0,1]
	v_pk_fma_f32 v[146:147], v[148:149], v[220:221], v[146:147]
	v_pk_fma_f32 v[130:131], v[150:151], v[228:229], v[146:147]
	v_lshlrev_b32_e32 v146, 16, v82
	v_and_b32_e32 v147, 0xffff0000, v82
	v_lshlrev_b32_e32 v148, 16, v94
	v_and_b32_e32 v149, 0xffff0000, v94
	v_lshlrev_b32_e32 v150, 16, v106
	v_and_b32_e32 v151, 0xffff0000, v106
	v_pk_add_f32 v[148:149], v[148:149], v[146:147] neg_lo:[0,1] neg_hi:[0,1]
	v_pk_add_f32 v[150:151], v[150:151], v[146:147] neg_lo:[0,1] neg_hi:[0,1]
	v_pk_fma_f32 v[146:147], v[148:149], v[222:223], v[146:147]
	v_pk_fma_f32 v[132:133], v[150:151], v[230:231], v[146:147]
	v_lshlrev_b32_e32 v146, 16, v83
	v_and_b32_e32 v147, 0xffff0000, v83
	v_lshlrev_b32_e32 v148, 16, v95
	v_and_b32_e32 v149, 0xffff0000, v95
	v_lshlrev_b32_e32 v150, 16, v107
	v_and_b32_e32 v151, 0xffff0000, v107
	v_pk_add_f32 v[148:149], v[148:149], v[146:147] neg_lo:[0,1] neg_hi:[0,1]
	v_pk_add_f32 v[150:151], v[150:151], v[146:147] neg_lo:[0,1] neg_hi:[0,1]
	v_pk_fma_f32 v[146:147], v[148:149], v[224:225], v[146:147]
	v_pk_fma_f32 v[134:135], v[150:151], v[232:233], v[146:147]
	v_lshlrev_b32_e32 v146, 16, v84
; DI float red8(float x) { x += dppf<0xB1>(x); x += dppf<0x4E>(x); x += dppf<0x141>(x); return x; }
; DI void shifted_load8(const bfr* P, int m, int t, int col, const float* mu, float (&o)[8]) {
;   const bfr* row = P + (size_t)m * PW + col;
;   const bool hp = (t != 0 && t != TL), hn = (t != TL - 1 && t != TT - 1);
;   const u32x4 cur = *(const u32x4*)row;
;   u32x4 prv = {0u, 0u, 0u, 0u}, nxt = {0u, 0u, 0u, 0u};
;   if (hp) prv = *(const u32x4*)(row - PW);
;   if (hn) nxt = *(const u32x4*)(row + PW);
;   float x[8], xp[8], xn[8], m0v[8], m1v[8];
;   unpack8(cur, x); unpack8(prv, xp); unpack8(nxt, xn);
;   load8f(mu + col, m0v); load8f(mu + 1152 + col, m1v);
; #pragma unroll
;   for (int e = 0; e < 8; ++e) o[e] = x[e] + m0v[e] * (xp[e] - x[e]) + m1v[e] * (xn[e] - x[e]);
; }
; DN void rw_finish_tile(const Params& p, int l, int tile, char* smem) {
;     ...
;     float sy = 0.f;
; #pragma unroll
;     for (int e = 0; e < 8; ++e) { y0[e] += y1[e]; sy += y0[e]; }
;     const float mean = red8(sy) * (1.f / 64.f);
;     float sv = 0.f, sd = 0.f;
; #pragma unroll
;     for (int e = 0; e < 8; ++e) {
;       const float dl = y0[e] - mean; y0[e] = dl; sv += dl * dl;
;       const float kds = kx[e] * (1.f + (af[e] - 1.f) * kaw[e]) + kx[e] * (1.f + (ab[e] - 1.f) * kaw[e]);
;       sd += rr[e] * rk[e] * kds;
;     }
;     const float var = red8(sv) * (1.f / 64.f);
	v_and_b32_e32 v147, 0xffff0000, v84
	v_lshlrev_b32_e32 v148, 16, v96
	v_and_b32_e32 v149, 0xffff0000, v96
	v_lshlrev_b32_e32 v150, 16, v108
	v_and_b32_e32 v151, 0xffff0000, v108
	v_pk_add_f32 v[148:149], v[148:149], v[146:147] neg_lo:[0,1] neg_hi:[0,1]
	v_pk_add_f32 v[150:151], v[150:151], v[146:147] neg_lo:[0,1] neg_hi:[0,1]
	v_pk_fma_f32 v[146:147], v[148:149], v[234:235], v[146:147]
	v_pk_fma_f32 v[136:137], v[150:151], v[242:243], v[146:147]
	v_lshlrev_b32_e32 v146, 16, v85
	v_and_b32_e32 v147, 0xffff0000, v85
	v_lshlrev_b32_e32 v148, 16, v97
	v_and_b32_e32 v149, 0xffff0000, v97
	v_lshlrev_b32_e32 v150, 16, v109
	v_and_b32_e32 v151, 0xffff0000, v109
	v_pk_add_f32 v[148:149], v[148:149], v[146:147] neg_lo:[0,1] neg_hi:[0,1]
	v_pk_add_f32 v[150:151], v[150:151], v[146:147] neg_lo:[0,1] neg_hi:[0,1]
	v_pk_fma_f32 v[146:147], v[148:149], v[236:237], v[146:147]
	v_pk_fma_f32 v[138:139], v[150:151], v[244:245], v[146:147]
	v_lshlrev_b32_e32 v146, 16, v86
	v_and_b32_e32 v147, 0xffff0000, v86
	v_lshlrev_b32_e32 v148, 16, v98
	v_and_b32_e32 v149, 0xffff0000, v98
	v_lshlrev_b32_e32 v150, 16, v110
	v_and_b32_e32 v151, 0xffff0000, v110
	v_pk_add_f32 v[148:149], v[148:149], v[146:147] neg_lo:[0,1] neg_hi:[0,1]
	v_pk_add_f32 v[150:151], v[150:151], v[146:147] neg_lo:[0,1] neg_hi:[0,1]
	v_pk_fma_f32 v[146:147], v[148:149], v[238:239], v[146:147]
	v_pk_fma_f32 v[140:141], v[150:151], v[246:247], v[146:147]
	v_lshlrev_b32_e32 v146, 16, v87
	v_and_b32_e32 v147, 0xffff0000, v87
	v_lshlrev_b32_e32 v148, 16, v99
	v_and_b32_e32 v149, 0xffff0000, v99
	v_lshlrev_b32_e32 v150, 16, v111
	v_and_b32_e32 v151, 0xffff0000, v111
	v_pk_add_f32 v[148:149], v[148:149], v[146:147] neg_lo:[0,1] neg_hi:[0,1]
	v_pk_add_f32 v[150:151], v[150:151], v[146:147] neg_lo:[0,1] neg_hi:[0,1]
	v_pk_fma_f32 v[146:147], v[148:149], v[240:241], v[146:147]
	v_pk_fma_f32 v[142:143], v[150:151], v[248:249], v[146:147]
	v_lshlrev_b32_e32 v146, 16, v56
	v_and_b32_e32 v147, 0xffff0000, v56
	v_lshlrev_b32_e32 v148, 16, v60
	v_and_b32_e32 v149, 0xffff0000, v60
	v_pk_add_f32 v[76:77], v[146:147], v[148:149]
	v_lshlrev_b32_e32 v146, 16, v57
	v_and_b32_e32 v147, 0xffff0000, v57
	v_lshlrev_b32_e32 v148, 16, v61
	v_and_b32_e32 v149, 0xffff0000, v61
	v_pk_add_f32 v[78:79], v[146:147], v[148:149]
	v_lshlrev_b32_e32 v146, 16, v58
	v_and_b32_e32 v147, 0xffff0000, v58
	v_lshlrev_b32_e32 v148, 16, v62
	v_and_b32_e32 v149, 0xffff0000, v62
	v_pk_add_f32 v[80:81], v[146:147], v[148:149]
	v_lshlrev_b32_e32 v146, 16, v59
	v_and_b32_e32 v147, 0xffff0000, v59
	v_lshlrev_b32_e32 v148, 16, v63
	v_and_b32_e32 v149, 0xffff0000, v63
	v_pk_add_f32 v[82:83], v[146:147], v[148:149]
	v_add_f32_e32 v152, 0, v76
	v_add_f32_e32 v152, v77, v152
	v_add_f32_e32 v152, v78, v152
	v_add_f32_e32 v152, v79, v152
	v_add_f32_e32 v152, v80, v152
	v_add_f32_e32 v152, v81, v152
	v_add_f32_e32 v152, v82, v152
	v_add_f32_e32 v152, v83, v152
	s_nop 1
	v_add_f32_dpp v152, v152, v152 quad_perm:[1,0,3,2] row_mask:0xf bank_mask:0xf bound_ctrl:1
	s_nop 1
	v_add_f32_dpp v152, v152, v152 quad_perm:[2,3,0,1] row_mask:0xf bank_mask:0xf bound_ctrl:1
	s_nop 1
	v_add_f32_dpp v152, v152, v152 row_half_mirror row_mask:0xf bank_mask:0xf bound_ctrl:1
	v_mul_f32_e32 v154, 0x3c800000, v152
	v_pk_add_f32 v[76:77], v[76:77], v[154:155] op_sel_hi:[1,0] neg_lo:[0,1] neg_hi:[0,1]
	v_pk_add_f32 v[78:79], v[78:79], v[154:155] op_sel_hi:[1,0] neg_lo:[0,1] neg_hi:[0,1]
	v_pk_add_f32 v[80:81], v[80:81], v[154:155] op_sel_hi:[1,0] neg_lo:[0,1] neg_hi:[0,1]
	v_pk_add_f32 v[82:83], v[82:83], v[154:155] op_sel_hi:[1,0] neg_lo:[0,1] neg_hi:[0,1]
	v_pk_mul_f32 v[146:147], v[76:77], v[76:77]
	v_add_f32_e32 v250, 0, v146
	v_add_f32_e32 v250, v147, v250
	v_pk_mul_f32 v[146:147], v[78:79], v[78:79]
	v_add_f32_e32 v250, v146, v250
	v_add_f32_e32 v250, v147, v250
	v_pk_mul_f32 v[146:147], v[80:81], v[80:81]
	v_add_f32_e32 v250, v146, v250
	v_add_f32_e32 v250, v147, v250
	v_pk_mul_f32 v[146:147], v[82:83], v[82:83]
	v_add_f32_e32 v250, v146, v250
	v_add_f32_e32 v250, v147, v250
	v_lshlrev_b32_e32 v146, 16, v64
	v_and_b32_e32 v147, 0xffff0000, v64
	v_lshlrev_b32_e32 v148, 16, v68
	v_and_b32_e32 v149, 0xffff0000, v68
	v_pk_add_f32 v[146:147], v[146:147], -1.0 op_sel_hi:[1,0]
	v_pk_add_f32 v[148:149], v[148:149], -1.0 op_sel_hi:[1,0]
	v_pk_fma_f32 v[146:147], v[112:113], v[146:147], 1.0 op_sel_hi:[1,1,0]
	v_pk_fma_f32 v[148:149], v[112:113], v[148:149], 1.0 op_sel_hi:[1,1,0]
	v_pk_mul_f32 v[146:147], v[146:147], v[128:129]
	v_pk_fma_f32 v[148:149], v[148:149], v[128:129], v[146:147]
	v_pk_mul_f32 v[150:151], v[172:173], v[120:121]
; DI unsigned pack2(float a, float b) { unsigned r; asm volatile("v_cvt_pk_bf16_f32 %0, %1, %2" : "=v"(r) : "v"(a), "v"(b)); return r; }
; DI float red8(float x) { x += dppf<0xB1>(x); x += dppf<0x4E>(x); x += dppf<0x141>(x); return x; }
; DN void rw_finish_tile(const Params& p, int l, int tile, char* smem) {
;     ...
;     for (int e = 0; e < 8; ++e) {
;       const float dl = y0[e] - mean; y0[e] = dl; sv += dl * dl;
;       const float kds = kx[e] * (1.f + (af[e] - 1.f) * kaw[e]) + kx[e] * (1.f + (ab[e] - 1.f) * kaw[e]);
;       sd += rr[e] * rk[e] * kds;
;     }
;     const float var = red8(sv) * (1.f / 64.f);
;     const float sdot = red8(sd);
;     const float rs = rsqrtf(var + 64e-5f);
;     float ov[8];
; #pragma unroll
;     for (int e = 0; e < 8; ++e) ov[e] = (y0[e] * rs * lng[e] + lnb[e] + sdot * vx[e]) * gt[e];
;     u32x4 ow; ow.x = pack2(ov[0], ov[1]); ow.y = pack2(ov[2], ov[3]); ow.z = pack2(ov[4], ov[5]); ow.w = pack2(ov[6], ov[7]);
;     *(u32x4*)(O + (size_t)m * DM + c0) = ow;
	v_pk_mul_f32 v[150:151], v[150:151], v[148:149]
	v_add_f32_e32 v251, 0, v150
	v_add_f32_e32 v251, v151, v251
	v_lshlrev_b32_e32 v146, 16, v65
	v_and_b32_e32 v147, 0xffff0000, v65
	v_lshlrev_b32_e32 v148, 16, v69
	v_and_b32_e32 v149, 0xffff0000, v69
	v_pk_add_f32 v[146:147], v[146:147], -1.0 op_sel_hi:[1,0]
	v_pk_add_f32 v[148:149], v[148:149], -1.0 op_sel_hi:[1,0]
	v_pk_fma_f32 v[146:147], v[114:115], v[146:147], 1.0 op_sel_hi:[1,1,0]
	v_pk_fma_f32 v[148:149], v[114:115], v[148:149], 1.0 op_sel_hi:[1,1,0]
	v_pk_mul_f32 v[146:147], v[146:147], v[130:131]
	v_pk_fma_f32 v[148:149], v[148:149], v[130:131], v[146:147]
	v_pk_mul_f32 v[150:151], v[174:175], v[122:123]
	v_pk_mul_f32 v[150:151], v[150:151], v[148:149]
	v_add_f32_e32 v251, v150, v251
	v_add_f32_e32 v251, v151, v251
	v_lshlrev_b32_e32 v146, 16, v66
	v_and_b32_e32 v147, 0xffff0000, v66
	v_lshlrev_b32_e32 v148, 16, v70
	v_and_b32_e32 v149, 0xffff0000, v70
	v_pk_add_f32 v[146:147], v[146:147], -1.0 op_sel_hi:[1,0]
	v_pk_add_f32 v[148:149], v[148:149], -1.0 op_sel_hi:[1,0]
	v_pk_fma_f32 v[146:147], v[116:117], v[146:147], 1.0 op_sel_hi:[1,1,0]
	v_pk_fma_f32 v[148:149], v[116:117], v[148:149], 1.0 op_sel_hi:[1,1,0]
	v_pk_mul_f32 v[146:147], v[146:147], v[132:133]
	v_pk_fma_f32 v[148:149], v[148:149], v[132:133], v[146:147]
	v_pk_mul_f32 v[150:151], v[176:177], v[124:125]
	v_pk_mul_f32 v[150:151], v[150:151], v[148:149]
	v_add_f32_e32 v251, v150, v251
	v_add_f32_e32 v251, v151, v251
	v_lshlrev_b32_e32 v146, 16, v67
	v_and_b32_e32 v147, 0xffff0000, v67
	v_lshlrev_b32_e32 v148, 16, v71
	v_and_b32_e32 v149, 0xffff0000, v71
	v_pk_add_f32 v[146:147], v[146:147], -1.0 op_sel_hi:[1,0]
	v_pk_add_f32 v[148:149], v[148:149], -1.0 op_sel_hi:[1,0]
	v_pk_fma_f32 v[146:147], v[118:119], v[146:147], 1.0 op_sel_hi:[1,1,0]
	v_pk_fma_f32 v[148:149], v[118:119], v[148:149], 1.0 op_sel_hi:[1,1,0]
	v_pk_mul_f32 v[146:147], v[146:147], v[134:135]
	v_pk_fma_f32 v[148:149], v[148:149], v[134:135], v[146:147]
	v_pk_mul_f32 v[150:151], v[178:179], v[126:127]
	v_pk_mul_f32 v[150:151], v[150:151], v[148:149]
	v_add_f32_e32 v251, v150, v251
	v_add_f32_e32 v251, v151, v251
	v_add_f32_dpp v250, v250, v250 quad_perm:[1,0,3,2] row_mask:0xf bank_mask:0xf bound_ctrl:1
	s_nop 0
	v_add_f32_dpp v251, v251, v251 quad_perm:[1,0,3,2] row_mask:0xf bank_mask:0xf bound_ctrl:1
	v_add_f32_dpp v250, v250, v250 quad_perm:[2,3,0,1] row_mask:0xf bank_mask:0xf bound_ctrl:1
	s_nop 0
	v_add_f32_dpp v251, v251, v251 quad_perm:[2,3,0,1] row_mask:0xf bank_mask:0xf bound_ctrl:1
	v_add_f32_dpp v250, v250, v250 row_half_mirror row_mask:0xf bank_mask:0xf bound_ctrl:1
	s_nop 0
	v_add_f32_dpp v251, v251, v251 row_half_mirror row_mask:0xf bank_mask:0xf bound_ctrl:1
	v_mov_b32_e32 v155, 0x3a27c5ac
	v_fmamk_f32 v250, v250, 0x3c800000, v155
	v_rsq_f32_e32 v250, v250
	v_mov_b32_e32 v152, v251
	v_pk_mul_f32 v[146:147], v[76:77], v[250:251] op_sel_hi:[1,0]
	v_pk_mul_f32 v[146:147], v[156:157], v[146:147]
	v_pk_add_f32 v[146:147], v[164:165], v[146:147]
	v_pk_mul_f32 v[148:149], v[136:137], v[152:153] op_sel_hi:[1,0]
	v_pk_add_f32 v[146:147], v[148:149], v[146:147]
	v_lshlrev_b32_e32 v148, 16, v72
	v_and_b32_e32 v149, 0xffff0000, v72
	v_pk_mul_f32 v[146:147], v[146:147], v[148:149]
	v_cvt_pk_bf16_f32 v72, v146, v147
	v_pk_mul_f32 v[146:147], v[78:79], v[250:251] op_sel_hi:[1,0]
	v_pk_mul_f32 v[146:147], v[158:159], v[146:147]
	v_pk_add_f32 v[146:147], v[166:167], v[146:147]
	v_pk_mul_f32 v[148:149], v[138:139], v[152:153] op_sel_hi:[1,0]
	v_pk_add_f32 v[146:147], v[148:149], v[146:147]
	v_lshlrev_b32_e32 v148, 16, v73
	v_and_b32_e32 v149, 0xffff0000, v73
	v_pk_mul_f32 v[146:147], v[146:147], v[148:149]
	v_cvt_pk_bf16_f32 v73, v146, v147
	v_pk_mul_f32 v[146:147], v[80:81], v[250:251] op_sel_hi:[1,0]
	v_pk_mul_f32 v[146:147], v[160:161], v[146:147]
	v_pk_add_f32 v[146:147], v[168:169], v[146:147]
	v_pk_mul_f32 v[148:149], v[140:141], v[152:153] op_sel_hi:[1,0]
	v_pk_add_f32 v[146:147], v[148:149], v[146:147]
	v_lshlrev_b32_e32 v148, 16, v74
	v_and_b32_e32 v149, 0xffff0000, v74
	v_pk_mul_f32 v[146:147], v[146:147], v[148:149]
	v_cvt_pk_bf16_f32 v74, v146, v147
	v_pk_mul_f32 v[146:147], v[82:83], v[250:251] op_sel_hi:[1,0]
	v_pk_mul_f32 v[146:147], v[162:163], v[146:147]
	v_pk_add_f32 v[146:147], v[170:171], v[146:147]
	v_pk_mul_f32 v[148:149], v[142:143], v[152:153] op_sel_hi:[1,0]
	v_pk_add_f32 v[146:147], v[148:149], v[146:147]
	v_lshlrev_b32_e32 v148, 16, v75
	v_and_b32_e32 v149, 0xffff0000, v75
	v_pk_mul_f32 v[146:147], v[146:147], v[148:149]
	v_cvt_pk_bf16_f32 v75, v146, v147
	global_store_dwordx4 v181, v[72:75], s[2:3]
	s_branch .LBB0_1000
